# v9 + packed v_pk_fma_f32 in fused attention softmax split into scalar fma (bit-identical)
# baseline (speedup 1.0000x reference)
.LBB0_742:
	s_add_i32 s27, s63, -3
	s_add_u32 s24, s76, s18
	s_addc_u32 s28, s77, s19
	s_add_u32 s10, s24, 0xe212000
	s_addc_u32 s11, s28, 0
	s_mul_i32 s25, s16, 0x6000
	v_lshl_add_u64 v[200:201], v[180:181], 1, s[10:11]
	s_add_i32 s12, s25, s49
	s_mov_b32 s13, m0
	s_mov_b32 m0, s12
	s_nop 0
	global_load_lds_dwordx4 v[200:201], off
	s_mov_b32 m0, s13
	v_lshl_add_u64 v[200:201], v[182:183], 1, s[10:11]
	s_mov_b32 s26, s16
	s_add_i32 s13, s12, 0x2000
	s_mov_b32 s16, m0
	s_mov_b32 m0, s13
	s_nop 0
	global_load_lds_dwordx4 v[200:201], off
	s_mov_b32 m0, s16
	v_lshl_add_u64 v[200:201], v[184:185], 1, s[10:11]
	s_add_i32 s10, s12, 0x4000
	s_add_u32 s29, s76, s20
	s_addc_u32 s30, s77, s21
	s_mov_b32 s11, m0
	s_mov_b32 m0, s10
	s_nop 0
	global_load_lds_dwordx4 v[200:201], off
	s_mov_b32 m0, s11
	s_add_u32 s10, s29, 0x14208000
	s_addc_u32 s11, s30, 0
	s_lshl_b32 s22, s4, 14
	s_add_i32 s12, s22, s51
	v_lshl_add_u64 v[200:201], v[186:187], 1, s[10:11]
	s_mov_b32 s13, m0
	s_mov_b32 m0, s12
	s_nop 0
	global_load_lds_dwordx4 v[200:201], off
	s_mov_b32 m0, s13
	v_lshl_add_u64 v[200:201], v[188:189], 1, s[10:11]
	s_add_i32 s10, s12, 0x2000
	s_mov_b32 s11, m0
	s_mov_b32 m0, s10
	s_nop 0
	global_load_lds_dwordx4 v[200:201], off
	s_mov_b32 m0, s11
	s_cmp_le_i32 s27, s52
	s_cselect_b64 s[12:13], -1, 0
	s_and_b64 vcc, exec, s[12:13]
	s_mul_i32 s31, s62, 0x6000
	s_cbranch_vccz .LBB0_745
	v_add_u32_e32 v232, s31, v206
	ds_read_b128 v[64:67], v232 offset:0
	ds_read_b128 v[68:71], v232 offset:12288
	v_add_u32_e32 v233, s31, v207
	ds_read_b128 v[200:203], v233 offset:0
	ds_read_b128 v[212:215], v233 offset:12288
	v_add_u32_e32 v234, s31, v208
	ds_read_b128 v[216:219], v234 offset:0
	ds_read_b128 v[220:223], v234 offset:12288
	s_waitcnt lgkmcnt(4)
	v_add_u32_e32 v235, s31, v209
	v_mfma_f32_32x32x16_bf16 v[80:95], v[64:67], v[172:175], 0
	v_add_f32_e32 v241, 0, v112
	v_add_f32_e32 v241, v113, v241
	v_add_f32_e32 v241, v114, v241
	v_add_f32_e32 v241, v115, v241
	ds_read_b128 v[224:227], v235 offset:0
	ds_read_b128 v[228:231], v235 offset:12288
	s_waitcnt lgkmcnt(4)
	v_mfma_f32_32x32x16_bf16 v[64:79], v[68:71], v[172:175], 0
	v_add_f32_e32 v241, v116, v241
	v_add_f32_e32 v241, v117, v241
	v_add_f32_e32 v241, v118, v241
	v_add_f32_e32 v241, v119, v241
	v_mfma_f32_32x32x16_bf16 v[80:95], v[200:203], v[168:171], v[80:95]
	v_add_f32_e32 v241, v120, v241
	v_add_f32_e32 v241, v121, v241
	v_add_f32_e32 v241, v122, v241
	v_add_f32_e32 v241, v123, v241
	ds_read_b128 v[200:203], v232 offset:128
	v_mfma_f32_32x32x16_bf16 v[64:79], v[212:215], v[168:171], v[64:79]
	v_exp_f32_e32 v96, v96
	v_add_f32_e32 v241, v124, v241
	v_exp_f32_e32 v97, v97
	v_add_f32_e32 v241, v125, v241
	ds_read_b128 v[212:215], v232 offset:12416
	s_waitcnt lgkmcnt(4)
	v_mfma_f32_32x32x16_bf16 v[80:95], v[216:219], v[164:167], v[80:95]
	v_exp_f32_e32 v98, v98
	v_add_f32_e32 v241, v126, v241
	v_exp_f32_e32 v99, v99
	v_add_f32_e32 v241, v127, v241
	ds_read_b128 v[216:219], v233 offset:128
	v_mfma_f32_32x32x16_bf16 v[64:79], v[220:223], v[164:167], v[64:79]
	v_exp_f32_e32 v100, v100
	v_add_f32_e32 v241, v96, v241
	v_exp_f32_e32 v101, v101
	v_add_f32_e32 v241, v97, v241
	ds_read_b128 v[220:223], v233 offset:12416
	s_waitcnt lgkmcnt(4)
	v_mfma_f32_32x32x16_bf16 v[80:95], v[224:227], v[160:163], v[80:95]
	v_exp_f32_e32 v102, v102
	v_add_f32_e32 v241, v98, v241
	v_exp_f32_e32 v103, v103
	v_add_f32_e32 v241, v99, v241
	ds_read_b128 v[224:227], v234 offset:128
	v_mfma_f32_32x32x16_bf16 v[64:79], v[228:231], v[160:163], v[64:79]
	v_exp_f32_e32 v104, v104
	v_add_f32_e32 v241, v100, v241
	v_exp_f32_e32 v105, v105
	v_add_f32_e32 v241, v101, v241
	ds_read_b128 v[228:231], v234 offset:12416
	s_waitcnt lgkmcnt(4)
	v_mfma_f32_32x32x16_bf16 v[80:95], v[200:203], v[156:159], v[80:95]
	v_exp_f32_e32 v106, v106
	v_add_f32_e32 v241, v102, v241
	v_exp_f32_e32 v107, v107
	ds_read_b128 v[200:203], v235 offset:128
	v_mfma_f32_32x32x16_bf16 v[64:79], v[212:215], v[156:159], v[64:79]
	v_add_f32_e32 v241, v103, v241
	v_exp_f32_e32 v108, v108
	v_add_f32_e32 v241, v104, v241
	ds_read_b128 v[212:215], v235 offset:12416
	s_waitcnt lgkmcnt(4)
	v_mfma_f32_32x32x16_bf16 v[80:95], v[216:219], v[152:155], v[80:95]
	v_exp_f32_e32 v109, v109
	v_add_f32_e32 v241, v105, v241
	v_exp_f32_e32 v110, v110
	ds_read_b128 v[216:219], v232 offset:256
	v_mfma_f32_32x32x16_bf16 v[64:79], v[220:223], v[152:155], v[64:79]
	v_add_f32_e32 v241, v106, v241
	v_exp_f32_e32 v111, v111
	v_add_f32_e32 v241, v107, v241
	ds_read_b128 v[220:223], v232 offset:12544
	s_waitcnt lgkmcnt(4)
	v_mfma_f32_32x32x16_bf16 v[80:95], v[224:227], v[148:151], v[80:95]
	v_add_f32_e32 v241, v108, v241
	v_add_f32_e32 v241, v109, v241
	v_add_f32_e32 v241, v110, v241
	ds_read_b128 v[224:227], v233 offset:256
	v_mfma_f32_32x32x16_bf16 v[64:79], v[228:231], v[148:151], v[64:79]
	v_add_f32_e32 v241, v111, v241
	v_mov_b32_e32 v242, v241
	v_cvt_pk_bf16_f32 v112, v112, v113
	ds_read_b128 v[228:231], v233 offset:12544
	s_waitcnt lgkmcnt(4)
	v_mfma_f32_32x32x16_bf16 v[80:95], v[200:203], v[144:147], v[80:95]
	v_cvt_pk_bf16_f32 v113, v114, v115
	v_permlane32_swap_b32_e32 v241, v242
	v_cvt_pk_bf16_f32 v114, v116, v117
	ds_read_b128 v[200:203], v234 offset:256
	v_mfma_f32_32x32x16_bf16 v[64:79], v[212:215], v[144:147], v[64:79]
	v_cvt_pk_bf16_f32 v115, v118, v119
	v_cvt_pk_bf16_f32 v116, v120, v121
	v_cvt_pk_bf16_f32 v117, v122, v123
	ds_read_b128 v[212:215], v234 offset:12544
	s_waitcnt lgkmcnt(4)
	v_mfma_f32_32x32x16_bf16 v[80:95], v[216:219], v[140:143], v[80:95]
	v_cvt_pk_bf16_f32 v118, v124, v125
	v_cvt_pk_bf16_f32 v119, v126, v127
	v_cvt_pk_bf16_f32 v96, v96, v97
	ds_read_b128 v[216:219], v235 offset:256
	v_mfma_f32_32x32x16_bf16 v[64:79], v[220:223], v[140:143], v[64:79]
	v_cvt_pk_bf16_f32 v97, v98, v99
	v_cvt_pk_bf16_f32 v98, v100, v101
	v_cvt_pk_bf16_f32 v99, v102, v103
	ds_read_b128 v[220:223], v235 offset:12544
	s_waitcnt lgkmcnt(4)
	v_mfma_f32_32x32x16_bf16 v[80:95], v[224:227], v[136:139], v[80:95]
	v_cvt_pk_bf16_f32 v100, v104, v105
	v_cvt_pk_bf16_f32 v101, v106, v107
	v_cvt_pk_bf16_f32 v102, v108, v109
	v_mfma_f32_32x32x16_bf16 v[64:79], v[228:231], v[136:139], v[64:79]
	v_cvt_pk_bf16_f32 v103, v110, v111
	v_add_f32_e32 v243, v241, v242
	v_fmac_f32_e32 v243, v210, v211
	s_waitcnt lgkmcnt(2)
	v_mfma_f32_32x32x16_bf16 v[80:95], v[200:203], v[132:135], v[80:95]
	v_permlane32_swap_b32_e32 v112, v114
	v_permlane32_swap_b32_e32 v113, v115
	v_permlane32_swap_b32_e32 v116, v118
	v_mfma_f32_32x32x16_bf16 v[64:79], v[212:215], v[132:135], v[64:79]
	v_permlane32_swap_b32_e32 v117, v119
	v_permlane32_swap_b32_e32 v96, v98
	v_permlane32_swap_b32_e32 v97, v99
	s_waitcnt lgkmcnt(0)
	v_mfma_f32_32x32x16_bf16 v[80:95], v[216:219], v[128:131], v[80:95]
	v_permlane32_swap_b32_e32 v100, v102
	v_permlane32_swap_b32_e32 v101, v103
	v_mov_b32_e32 v211, v243
	v_mfma_f32_32x32x16_bf16 v[64:79], v[220:223], v[128:131], v[64:79]
	v_lshl_add_u32 v244, s26, 14, v196
	ds_read_b64_tr_b16 v[224:225], v244 offset:0
	ds_read_b64_tr_b16 v[226:227], v244 offset:2048
	ds_read_b64_tr_b16 v[228:229], v244 offset:512
	ds_read_b64_tr_b16 v[230:231], v244 offset:2560
	ds_read_b64_tr_b16 v[232:233], v244 offset:1024
	ds_read_b64_tr_b16 v[234:235], v244 offset:3072
	ds_read_b64_tr_b16 v[236:237], v244 offset:1536
	ds_read_b64_tr_b16 v[238:239], v244 offset:3584
	s_waitcnt lgkmcnt(0)
	v_mfma_f32_32x32x16_bf16 v[32:47], v[112:115], v[224:227], v[32:47]
	v_max_f32_e32 v246, v81, v81
	v_max_f32_e32 v247, v80, v80
	v_max_f32_e32 v246, v247, v246
	v_max3_f32 v246, v246, v82, v83
	v_max3_f32 v246, v246, v84, v85
	ds_read_b64_tr_b16 v[200:201], v244 offset:4096
	ds_read_b64_tr_b16 v[202:203], v244 offset:6144
	ds_read_b64_tr_b16 v[212:213], v244 offset:4608
	ds_read_b64_tr_b16 v[214:215], v244 offset:6656
	ds_read_b64_tr_b16 v[216:217], v244 offset:5120
	ds_read_b64_tr_b16 v[218:219], v244 offset:7168
	ds_read_b64_tr_b16 v[220:221], v244 offset:5632
	ds_read_b64_tr_b16 v[222:223], v244 offset:7680
	v_mfma_f32_32x32x16_bf16 v[48:63], v[112:115], v[228:231], v[48:63]
	v_max3_f32 v246, v246, v86, v87
	v_max3_f32 v246, v246, v88, v89
	v_max3_f32 v246, v246, v90, v91
	v_max3_f32 v246, v246, v92, v93
	v_max3_f32 v246, v246, v94, v95
	v_mfma_f32_32x32x16_bf16 v[0:15], v[112:115], v[232:235], v[0:15]
	v_max3_f32 v246, v246, v64, v65
	v_max3_f32 v246, v246, v66, v67
	v_max3_f32 v246, v246, v68, v69
	v_max3_f32 v246, v246, v70, v71
	v_max3_f32 v246, v246, v72, v73
	v_mfma_f32_32x32x16_bf16 v[16:31], v[112:115], v[236:239], v[16:31]
	v_max3_f32 v246, v246, v74, v75
	v_max3_f32 v246, v246, v76, v77
	v_max3_f32 v246, v246, v78, v79
	v_mov_b32_e32 v247, v246
	s_nop 1
	v_permlane32_swap_b32_e32 v246, v247
	s_waitcnt lgkmcnt(0)
	v_mfma_f32_32x32x16_bf16 v[32:47], v[116:119], v[200:203], v[32:47]
	v_max_f32_e32 v247, v247, v247
	v_max_f32_e32 v246, v246, v246
	v_max_f32_e32 v246, v246, v247
	v_sub_f32_e32 v247, v246, v204
	v_cmp_ge_f32_e32 vcc, s0, v247
	ds_read_b64_tr_b16 v[224:225], v244 offset:8192
	ds_read_b64_tr_b16 v[226:227], v244 offset:10240
	ds_read_b64_tr_b16 v[228:229], v244 offset:8704
	ds_read_b64_tr_b16 v[230:231], v244 offset:10752
	ds_read_b64_tr_b16 v[232:233], v244 offset:9216
	ds_read_b64_tr_b16 v[234:235], v244 offset:11264
	ds_read_b64_tr_b16 v[236:237], v244 offset:9728
	ds_read_b64_tr_b16 v[238:239], v244 offset:11776
	v_mfma_f32_32x32x16_bf16 v[48:63], v[116:119], v[212:215], v[48:63]
	v_max_f32_e32 v247, v204, v204
	v_max_f32_e32 v248, v247, v246
	v_sub_f32_e32 v246, v204, v248
	v_mul_f32_e32 v246, 0x3dd53b94, v246
	v_exp_f32_e32 v246, v246
	v_mfma_f32_32x32x16_bf16 v[0:15], v[116:119], v[216:219], v[0:15]
	s_cmp_eq_u64 vcc, exec
	s_cselect_b64 s[12:13], -1, 0
	v_cndmask_b32_e64 v205, v246, 1.0, s[12:13]
	v_cndmask_b32_e64 v204, v248, v204, s[12:13]
	v_mul_f32_e32 v246, 0xbdd53b94, v204
	v_mov_b32_e32 v247, v246
	v_fmamk_f32 v80, v80, 0x3dd53b94, v246
	v_mfma_f32_32x32x16_bf16 v[16:31], v[116:119], v[220:223], v[16:31]
	v_fmamk_f32 v81, v81, 0x3dd53b94, v246
	v_fmamk_f32 v82, v82, 0x3dd53b94, v246
	v_fmamk_f32 v83, v83, 0x3dd53b94, v246
	v_fmamk_f32 v84, v84, 0x3dd53b94, v246
	v_fmamk_f32 v85, v85, 0x3dd53b94, v246
	s_waitcnt lgkmcnt(0)
	v_mfma_f32_32x32x16_bf16 v[32:47], v[96:99], v[224:227], v[32:47]
	v_fmamk_f32 v86, v86, 0x3dd53b94, v246
	v_fmamk_f32 v87, v87, 0x3dd53b94, v246
	v_fmamk_f32 v88, v88, 0x3dd53b94, v246
	v_fmamk_f32 v89, v89, 0x3dd53b94, v246
	v_fmamk_f32 v90, v90, 0x3dd53b94, v246
	ds_read_b64_tr_b16 v[200:201], v244 offset:12288
	ds_read_b64_tr_b16 v[202:203], v244 offset:14336
	ds_read_b64_tr_b16 v[212:213], v244 offset:12800
	ds_read_b64_tr_b16 v[214:215], v244 offset:14848
	ds_read_b64_tr_b16 v[216:217], v244 offset:13312
	ds_read_b64_tr_b16 v[218:219], v244 offset:15360
	ds_read_b64_tr_b16 v[220:221], v244 offset:13824
	ds_read_b64_tr_b16 v[222:223], v244 offset:15872
	v_mfma_f32_32x32x16_bf16 v[48:63], v[96:99], v[228:231], v[48:63]
	v_fmamk_f32 v91, v91, 0x3dd53b94, v246
	v_fmamk_f32 v92, v92, 0x3dd53b94, v246
	v_fmamk_f32 v93, v93, 0x3dd53b94, v246
	v_fmamk_f32 v94, v94, 0x3dd53b94, v246
	v_fmac_f32_e32 v247, 0x3dd53b94, v95
	v_mfma_f32_32x32x16_bf16 v[0:15], v[96:99], v[232:235], v[0:15]
	v_exp_f32_e32 v80, v80
	v_exp_f32_e32 v81, v81
	v_exp_f32_e32 v82, v82
	v_exp_f32_e32 v83, v83
	v_exp_f32_e32 v84, v84
	v_mfma_f32_32x32x16_bf16 v[16:31], v[96:99], v[236:239], v[16:31]
	v_exp_f32_e32 v85, v85
	v_exp_f32_e32 v86, v86
	v_exp_f32_e32 v87, v87
	v_exp_f32_e32 v88, v88
	v_exp_f32_e32 v89, v89
	s_waitcnt lgkmcnt(0)
	v_mfma_f32_32x32x16_bf16 v[32:47], v[100:103], v[200:203], v[32:47]
	v_exp_f32_e32 v90, v90
	v_exp_f32_e32 v91, v91
	v_exp_f32_e32 v92, v92
	v_exp_f32_e32 v93, v93
	v_exp_f32_e32 v94, v94
	v_mfma_f32_32x32x16_bf16 v[48:63], v[100:103], v[212:215], v[48:63]
	v_exp_f32_e32 v95, v247
	v_fmamk_f32 v78, v78, 0x3dd53b94, v246
	v_fmamk_f32 v79, v79, 0x3dd53b94, v246
	v_fmamk_f32 v76, v76, 0x3dd53b94, v246
	v_fmamk_f32 v77, v77, 0x3dd53b94, v246
	v_mfma_f32_32x32x16_bf16 v[0:15], v[100:103], v[216:219], v[0:15]
	v_fmamk_f32 v74, v74, 0x3dd53b94, v246
	v_fmamk_f32 v75, v75, 0x3dd53b94, v246
	v_fmamk_f32 v72, v72, 0x3dd53b94, v246
	v_fmamk_f32 v73, v73, 0x3dd53b94, v246
	v_fmamk_f32 v70, v70, 0x3dd53b94, v246
	v_mfma_f32_32x32x16_bf16 v[16:31], v[100:103], v[220:223], v[16:31]
	v_fmamk_f32 v71, v71, 0x3dd53b94, v246
	v_fmamk_f32 v68, v68, 0x3dd53b94, v246
	v_fmamk_f32 v69, v69, 0x3dd53b94, v246
	v_fmamk_f32 v66, v66, 0x3dd53b94, v246
	v_fmamk_f32 v67, v67, 0x3dd53b94, v246
	v_fmamk_f32 v64, v64, 0x3dd53b94, v246
	v_fmamk_f32 v65, v65, 0x3dd53b94, v246
	s_mov_b64 s[10:11], 0
	v_cmp_gt_f32_e32 vcc, 1.0, v205
	s_cbranch_vccz .LBB0_752
	s_nop 7
	s_nop 4
	s_and_saveexec_b64 s[16:17], s[8:9]
	ds_write_b32 v195, v205 offset:128
	s_or_b64 exec, exec, s[16:17]
	s_waitcnt lgkmcnt(0)
	v_add_u32_e32 v213, s48, v176
	ds_read_b128 v[200:203], v213 offset:224
	ds_read_b128 v[214:217], v213 offset:192
	ds_read_b128 v[218:221], v213 offset:160
	ds_read_b128 v[222:225], v213 offset:128
	s_waitcnt lgkmcnt(3)
	v_pk_mul_f32 v[44:45], v[44:45], v[200:201]
	s_waitcnt lgkmcnt(2)
	v_pk_mul_f32 v[40:41], v[40:41], v[214:215]
	s_waitcnt lgkmcnt(1)
	v_pk_mul_f32 v[36:37], v[36:37], v[218:219]
	v_pk_mul_f32 v[46:47], v[46:47], v[202:203]
	v_pk_mul_f32 v[42:43], v[42:43], v[216:217]
	v_pk_mul_f32 v[38:39], v[38:39], v[220:221]
	s_waitcnt lgkmcnt(0)
	v_pk_mul_f32 v[34:35], v[34:35], v[224:225]
	v_pk_mul_f32 v[32:33], v[32:33], v[222:223]
	v_pk_mul_f32 v[60:61], v[60:61], v[200:201]
	v_pk_mul_f32 v[56:57], v[56:57], v[214:215]
	v_pk_mul_f32 v[52:53], v[52:53], v[218:219]
	v_pk_mul_f32 v[62:63], v[62:63], v[202:203]
	v_pk_mul_f32 v[58:59], v[58:59], v[216:217]
	v_pk_mul_f32 v[54:55], v[54:55], v[220:221]
	v_pk_mul_f32 v[50:51], v[50:51], v[224:225]
	v_pk_mul_f32 v[48:49], v[48:49], v[222:223]
	v_pk_mul_f32 v[12:13], v[12:13], v[200:201]
	v_pk_mul_f32 v[8:9], v[8:9], v[214:215]
	v_pk_mul_f32 v[4:5], v[4:5], v[218:219]
	v_pk_mul_f32 v[14:15], v[14:15], v[202:203]
	v_pk_mul_f32 v[10:11], v[10:11], v[216:217]
	v_pk_mul_f32 v[6:7], v[6:7], v[220:221]
	v_pk_mul_f32 v[2:3], v[2:3], v[224:225]
	v_pk_mul_f32 v[0:1], v[0:1], v[222:223]
	v_pk_mul_f32 v[28:29], v[28:29], v[200:201]
	v_pk_mul_f32 v[24:25], v[24:25], v[214:215]
	v_pk_mul_f32 v[20:21], v[20:21], v[218:219]
	v_pk_mul_f32 v[30:31], v[30:31], v[202:203]
	v_pk_mul_f32 v[26:27], v[26:27], v[216:217]
	v_pk_mul_f32 v[22:23], v[22:23], v[220:221]
	v_pk_mul_f32 v[18:19], v[18:19], v[224:225]
	v_pk_mul_f32 v[16:17], v[16:17], v[222:223]
	s_branch .LBB0_752

.LBB0_754:
	s_add_u32 s16, s29, 0x1420c000
	s_addc_u32 s17, s30, 0
	s_lshl_b32 s24, s26, 14
	s_add_i32 s28, s24, s51
	v_lshl_add_u64 v[200:201], v[186:187], 1, s[16:17]
	s_mov_b32 s29, m0
	s_mov_b32 m0, s28
	s_nop 0
	global_load_lds_dwordx4 v[200:201], off
	s_mov_b32 m0, s29
	s_addk_i32 s28, 0x2000
	s_cmp_lt_i32 s27, s52
	v_lshl_add_u64 v[200:201], v[188:189], 1, s[16:17]
	s_cselect_b64 s[16:17], -1, 0
	s_cmp_ge_i32 s27, s52
	s_mov_b32 s27, m0
	s_mov_b32 m0, s28
	s_nop 0
	global_load_lds_dwordx4 v[200:201], off
	s_mov_b32 m0, s27
	s_cbranch_scc1 .LBB0_766
	s_mul_i32 s27, s4, 0x6000
	v_add_u32_e32 v232, s27, v206
	ds_read_b128 v[96:99], v232 offset:0
	ds_read_b128 v[100:103], v232 offset:12288
	v_add_u32_e32 v233, s27, v207
	ds_read_b128 v[200:203], v233 offset:0
	ds_read_b128 v[212:215], v233 offset:12288
	v_add_u32_e32 v234, s27, v208
	ds_read_b128 v[216:219], v234 offset:0
	ds_read_b128 v[220:223], v234 offset:12288
	s_waitcnt lgkmcnt(4)
	v_add_u32_e32 v235, s27, v209
	v_mfma_f32_32x32x16_bf16 v[112:127], v[96:99], v[172:175], 0
	v_add_f32_e32 v241, 0, v80
	v_add_f32_e32 v241, v81, v241
	v_add_f32_e32 v241, v82, v241
	v_add_f32_e32 v241, v83, v241
	ds_read_b128 v[224:227], v235 offset:0
	ds_read_b128 v[228:231], v235 offset:12288
	s_waitcnt lgkmcnt(4)
	v_mfma_f32_32x32x16_bf16 v[96:111], v[100:103], v[172:175], 0
	v_add_f32_e32 v241, v84, v241
	v_add_f32_e32 v241, v85, v241
	v_add_f32_e32 v241, v86, v241
	v_add_f32_e32 v241, v87, v241
	v_mfma_f32_32x32x16_bf16 v[112:127], v[200:203], v[168:171], v[112:127]
	v_add_f32_e32 v241, v88, v241
	v_add_f32_e32 v241, v89, v241
	v_add_f32_e32 v241, v90, v241
	v_add_f32_e32 v241, v91, v241
	ds_read_b128 v[200:203], v232 offset:128
	v_mfma_f32_32x32x16_bf16 v[96:111], v[212:215], v[168:171], v[96:111]
	v_exp_f32_e32 v64, v64
	v_add_f32_e32 v241, v92, v241
	v_exp_f32_e32 v65, v65
	v_add_f32_e32 v241, v93, v241
	ds_read_b128 v[212:215], v232 offset:12416
	s_waitcnt lgkmcnt(4)
	v_mfma_f32_32x32x16_bf16 v[112:127], v[216:219], v[164:167], v[112:127]
	v_exp_f32_e32 v66, v66
	v_add_f32_e32 v241, v94, v241
	v_exp_f32_e32 v67, v67
	v_add_f32_e32 v241, v95, v241
	ds_read_b128 v[216:219], v233 offset:128
	v_mfma_f32_32x32x16_bf16 v[96:111], v[220:223], v[164:167], v[96:111]
	v_exp_f32_e32 v68, v68
	v_add_f32_e32 v241, v64, v241
	v_exp_f32_e32 v69, v69
	v_add_f32_e32 v241, v65, v241
	ds_read_b128 v[220:223], v233 offset:12416
	s_waitcnt lgkmcnt(4)
	v_mfma_f32_32x32x16_bf16 v[112:127], v[224:227], v[160:163], v[112:127]
	v_exp_f32_e32 v70, v70
	v_add_f32_e32 v241, v66, v241
	v_exp_f32_e32 v71, v71
	v_add_f32_e32 v241, v67, v241
	ds_read_b128 v[224:227], v234 offset:128
	v_mfma_f32_32x32x16_bf16 v[96:111], v[228:231], v[160:163], v[96:111]
	v_exp_f32_e32 v72, v72
	v_add_f32_e32 v241, v68, v241
	v_exp_f32_e32 v73, v73
	v_add_f32_e32 v241, v69, v241
	ds_read_b128 v[228:231], v234 offset:12416
	s_waitcnt lgkmcnt(4)
	v_mfma_f32_32x32x16_bf16 v[112:127], v[200:203], v[156:159], v[112:127]
	v_exp_f32_e32 v74, v74
	v_add_f32_e32 v241, v70, v241
	v_exp_f32_e32 v75, v75
	ds_read_b128 v[200:203], v235 offset:128
	v_mfma_f32_32x32x16_bf16 v[96:111], v[212:215], v[156:159], v[96:111]
	v_add_f32_e32 v241, v71, v241
	v_exp_f32_e32 v76, v76
	v_add_f32_e32 v241, v72, v241
	ds_read_b128 v[212:215], v235 offset:12416
	s_waitcnt lgkmcnt(4)
	v_mfma_f32_32x32x16_bf16 v[112:127], v[216:219], v[152:155], v[112:127]
	v_exp_f32_e32 v77, v77
	v_add_f32_e32 v241, v73, v241
	v_exp_f32_e32 v78, v78
	ds_read_b128 v[216:219], v232 offset:256
	v_mfma_f32_32x32x16_bf16 v[96:111], v[220:223], v[152:155], v[96:111]
	v_add_f32_e32 v241, v74, v241
	v_exp_f32_e32 v79, v79
	v_add_f32_e32 v241, v75, v241
	ds_read_b128 v[220:223], v232 offset:12544
	s_waitcnt lgkmcnt(4)
	v_mfma_f32_32x32x16_bf16 v[112:127], v[224:227], v[148:151], v[112:127]
	v_add_f32_e32 v241, v76, v241
	v_add_f32_e32 v241, v77, v241
	v_add_f32_e32 v241, v78, v241
	ds_read_b128 v[224:227], v233 offset:256
	v_mfma_f32_32x32x16_bf16 v[96:111], v[228:231], v[148:151], v[96:111]
	v_add_f32_e32 v241, v79, v241
	v_mov_b32_e32 v242, v241
	v_cvt_pk_bf16_f32 v80, v80, v81
	ds_read_b128 v[228:231], v233 offset:12544
	s_waitcnt lgkmcnt(4)
	v_mfma_f32_32x32x16_bf16 v[112:127], v[200:203], v[144:147], v[112:127]
	v_cvt_pk_bf16_f32 v81, v82, v83
	v_permlane32_swap_b32_e32 v241, v242
	v_cvt_pk_bf16_f32 v82, v84, v85
	ds_read_b128 v[200:203], v234 offset:256
	v_mfma_f32_32x32x16_bf16 v[96:111], v[212:215], v[144:147], v[96:111]
	v_cvt_pk_bf16_f32 v83, v86, v87
	v_cvt_pk_bf16_f32 v84, v88, v89
	v_cvt_pk_bf16_f32 v85, v90, v91
	ds_read_b128 v[212:215], v234 offset:12544
	s_waitcnt lgkmcnt(4)
	v_mfma_f32_32x32x16_bf16 v[112:127], v[216:219], v[140:143], v[112:127]
	v_cvt_pk_bf16_f32 v86, v92, v93
	v_cvt_pk_bf16_f32 v87, v94, v95
	v_cvt_pk_bf16_f32 v64, v64, v65
	ds_read_b128 v[216:219], v235 offset:256
	v_mfma_f32_32x32x16_bf16 v[96:111], v[220:223], v[140:143], v[96:111]
	v_cvt_pk_bf16_f32 v65, v66, v67
	v_cvt_pk_bf16_f32 v66, v68, v69
	v_cvt_pk_bf16_f32 v67, v70, v71
	ds_read_b128 v[220:223], v235 offset:12544
	s_waitcnt lgkmcnt(4)
	v_mfma_f32_32x32x16_bf16 v[112:127], v[224:227], v[136:139], v[112:127]
	v_cvt_pk_bf16_f32 v68, v72, v73
	v_cvt_pk_bf16_f32 v69, v74, v75
	v_cvt_pk_bf16_f32 v70, v76, v77
	v_mfma_f32_32x32x16_bf16 v[96:111], v[228:231], v[136:139], v[96:111]
	v_cvt_pk_bf16_f32 v71, v78, v79
	v_add_f32_e32 v243, v241, v242
	v_fmac_f32_e32 v243, v205, v211
	s_waitcnt lgkmcnt(2)
	v_mfma_f32_32x32x16_bf16 v[112:127], v[200:203], v[132:135], v[112:127]
	v_permlane32_swap_b32_e32 v80, v82
	v_permlane32_swap_b32_e32 v81, v83
	v_permlane32_swap_b32_e32 v84, v86
	v_mfma_f32_32x32x16_bf16 v[96:111], v[212:215], v[132:135], v[96:111]
	v_permlane32_swap_b32_e32 v85, v87
	v_permlane32_swap_b32_e32 v64, v66
	v_permlane32_swap_b32_e32 v65, v67
	s_waitcnt lgkmcnt(0)
	v_mfma_f32_32x32x16_bf16 v[112:127], v[216:219], v[128:131], v[112:127]
	v_permlane32_swap_b32_e32 v68, v70
	v_permlane32_swap_b32_e32 v69, v71
	v_mov_b32_e32 v211, v243
	v_mfma_f32_32x32x16_bf16 v[96:111], v[220:223], v[128:131], v[96:111]
	v_lshl_add_u32 v244, s62, 14, v196
	ds_read_b64_tr_b16 v[224:225], v244 offset:0
	ds_read_b64_tr_b16 v[226:227], v244 offset:2048
	ds_read_b64_tr_b16 v[228:229], v244 offset:512
	ds_read_b64_tr_b16 v[230:231], v244 offset:2560
	ds_read_b64_tr_b16 v[232:233], v244 offset:1024
	ds_read_b64_tr_b16 v[234:235], v244 offset:3072
	ds_read_b64_tr_b16 v[236:237], v244 offset:1536
	ds_read_b64_tr_b16 v[238:239], v244 offset:3584
	s_waitcnt lgkmcnt(0)
	v_mfma_f32_32x32x16_bf16 v[32:47], v[80:83], v[224:227], v[32:47]
	v_max_f32_e32 v246, v113, v113
	v_max_f32_e32 v247, v112, v112
	v_max_f32_e32 v246, v247, v246
	v_max3_f32 v246, v246, v114, v115
	v_max3_f32 v246, v246, v116, v117
	ds_read_b64_tr_b16 v[200:201], v244 offset:4096
	ds_read_b64_tr_b16 v[202:203], v244 offset:6144
	ds_read_b64_tr_b16 v[212:213], v244 offset:4608
	ds_read_b64_tr_b16 v[214:215], v244 offset:6656
	ds_read_b64_tr_b16 v[216:217], v244 offset:5120
	ds_read_b64_tr_b16 v[218:219], v244 offset:7168
	ds_read_b64_tr_b16 v[220:221], v244 offset:5632
	ds_read_b64_tr_b16 v[222:223], v244 offset:7680
	v_mfma_f32_32x32x16_bf16 v[48:63], v[80:83], v[228:231], v[48:63]
	v_max3_f32 v246, v246, v118, v119
	v_max3_f32 v246, v246, v120, v121
	v_max3_f32 v246, v246, v122, v123
	v_max3_f32 v246, v246, v124, v125
	v_max3_f32 v246, v246, v126, v127
	v_mfma_f32_32x32x16_bf16 v[0:15], v[80:83], v[232:235], v[0:15]
	v_max3_f32 v246, v246, v96, v97
	v_max3_f32 v246, v246, v98, v99
	v_max3_f32 v246, v246, v100, v101
	v_max3_f32 v246, v246, v102, v103
	v_max3_f32 v246, v246, v104, v105
	v_mfma_f32_32x32x16_bf16 v[16:31], v[80:83], v[236:239], v[16:31]
	v_max3_f32 v246, v246, v106, v107
	v_max3_f32 v246, v246, v108, v109
	v_max3_f32 v246, v246, v110, v111
	v_mov_b32_e32 v247, v246
	s_nop 1
	v_permlane32_swap_b32_e32 v246, v247
	s_waitcnt lgkmcnt(0)
	v_mfma_f32_32x32x16_bf16 v[32:47], v[84:87], v[200:203], v[32:47]
	v_max_f32_e32 v247, v247, v247
	v_max_f32_e32 v246, v246, v246
	v_max_f32_e32 v246, v246, v247
	v_sub_f32_e32 v247, v246, v204
	v_cmp_ge_f32_e32 vcc, s0, v247
	ds_read_b64_tr_b16 v[224:225], v244 offset:8192
	ds_read_b64_tr_b16 v[226:227], v244 offset:10240
	ds_read_b64_tr_b16 v[228:229], v244 offset:8704
	ds_read_b64_tr_b16 v[230:231], v244 offset:10752
	ds_read_b64_tr_b16 v[232:233], v244 offset:9216
	ds_read_b64_tr_b16 v[234:235], v244 offset:11264
	ds_read_b64_tr_b16 v[236:237], v244 offset:9728
	ds_read_b64_tr_b16 v[238:239], v244 offset:11776
	v_mfma_f32_32x32x16_bf16 v[48:63], v[84:87], v[212:215], v[48:63]
	v_max_f32_e32 v247, v204, v204
	v_max_f32_e32 v248, v247, v246
	v_sub_f32_e32 v246, v204, v248
	v_mul_f32_e32 v246, 0x3dd53b94, v246
	v_exp_f32_e32 v246, v246
	v_mfma_f32_32x32x16_bf16 v[0:15], v[84:87], v[216:219], v[0:15]
	s_cmp_eq_u64 vcc, exec
	s_cselect_b64 s[10:11], -1, 0
	v_cndmask_b32_e64 v210, v246, 1.0, s[10:11]
	v_cndmask_b32_e64 v204, v248, v204, s[10:11]
	v_mul_f32_e32 v246, 0xbdd53b94, v204
	v_mov_b32_e32 v247, v246
	v_fmamk_f32 v112, v112, 0x3dd53b94, v246
	v_mfma_f32_32x32x16_bf16 v[16:31], v[84:87], v[220:223], v[16:31]
	v_fmamk_f32 v113, v113, 0x3dd53b94, v246
	v_fmamk_f32 v114, v114, 0x3dd53b94, v246
	v_fmamk_f32 v115, v115, 0x3dd53b94, v246
	v_fmamk_f32 v116, v116, 0x3dd53b94, v246
	v_fmamk_f32 v117, v117, 0x3dd53b94, v246
	s_waitcnt lgkmcnt(0)
	v_mfma_f32_32x32x16_bf16 v[32:47], v[64:67], v[224:227], v[32:47]
	v_fmamk_f32 v118, v118, 0x3dd53b94, v246
	v_fmamk_f32 v119, v119, 0x3dd53b94, v246
	v_fmamk_f32 v120, v120, 0x3dd53b94, v246
	v_fmamk_f32 v121, v121, 0x3dd53b94, v246
	v_fmamk_f32 v122, v122, 0x3dd53b94, v246
	ds_read_b64_tr_b16 v[200:201], v244 offset:12288
	ds_read_b64_tr_b16 v[202:203], v244 offset:14336
	ds_read_b64_tr_b16 v[212:213], v244 offset:12800
	ds_read_b64_tr_b16 v[214:215], v244 offset:14848
	ds_read_b64_tr_b16 v[216:217], v244 offset:13312
	ds_read_b64_tr_b16 v[218:219], v244 offset:15360
	ds_read_b64_tr_b16 v[220:221], v244 offset:13824
	ds_read_b64_tr_b16 v[222:223], v244 offset:15872
	v_mfma_f32_32x32x16_bf16 v[48:63], v[64:67], v[228:231], v[48:63]
	v_fmamk_f32 v123, v123, 0x3dd53b94, v246
	v_fmamk_f32 v124, v124, 0x3dd53b94, v246
	v_fmamk_f32 v125, v125, 0x3dd53b94, v246
	v_fmamk_f32 v126, v126, 0x3dd53b94, v246
	v_fmac_f32_e32 v247, 0x3dd53b94, v127
	v_mfma_f32_32x32x16_bf16 v[0:15], v[64:67], v[232:235], v[0:15]
	v_exp_f32_e32 v112, v112
	v_exp_f32_e32 v113, v113
	v_exp_f32_e32 v114, v114
	v_exp_f32_e32 v115, v115
	v_exp_f32_e32 v116, v116
	v_mfma_f32_32x32x16_bf16 v[16:31], v[64:67], v[236:239], v[16:31]
	v_exp_f32_e32 v117, v117
	v_exp_f32_e32 v118, v118
	v_exp_f32_e32 v119, v119
	v_exp_f32_e32 v120, v120
	v_exp_f32_e32 v121, v121
	s_waitcnt lgkmcnt(0)
	v_mfma_f32_32x32x16_bf16 v[32:47], v[68:71], v[200:203], v[32:47]
	v_exp_f32_e32 v122, v122
	v_exp_f32_e32 v123, v123
	v_exp_f32_e32 v124, v124
	v_exp_f32_e32 v125, v125
	v_exp_f32_e32 v126, v126
	v_mfma_f32_32x32x16_bf16 v[48:63], v[68:71], v[212:215], v[48:63]
	v_exp_f32_e32 v127, v247
	v_fmamk_f32 v110, v110, 0x3dd53b94, v246
	v_fmamk_f32 v111, v111, 0x3dd53b94, v246
	v_fmamk_f32 v108, v108, 0x3dd53b94, v246
	v_fmamk_f32 v109, v109, 0x3dd53b94, v246
	v_mfma_f32_32x32x16_bf16 v[0:15], v[68:71], v[216:219], v[0:15]
	v_fmamk_f32 v106, v106, 0x3dd53b94, v246
	v_fmamk_f32 v107, v107, 0x3dd53b94, v246
	v_fmamk_f32 v104, v104, 0x3dd53b94, v246
	v_fmamk_f32 v105, v105, 0x3dd53b94, v246
	v_fmamk_f32 v102, v102, 0x3dd53b94, v246
	v_mfma_f32_32x32x16_bf16 v[16:31], v[68:71], v[220:223], v[16:31]
	v_fmamk_f32 v103, v103, 0x3dd53b94, v246
	v_fmamk_f32 v100, v100, 0x3dd53b94, v246
	v_fmamk_f32 v101, v101, 0x3dd53b94, v246
	v_fmamk_f32 v98, v98, 0x3dd53b94, v246
	v_fmamk_f32 v99, v99, 0x3dd53b94, v246
	v_fmamk_f32 v96, v96, 0x3dd53b94, v246
	v_fmamk_f32 v97, v97, 0x3dd53b94, v246
	v_cmp_gt_f32_e32 vcc, 1.0, v210
	s_cbranch_vccz .Lh2_tail
	s_nop 7
	s_nop 4
	s_and_saveexec_b64 s[16:17], s[8:9]
	ds_write_b32 v195, v210 offset:128
	s_or_b64 exec, exec, s[16:17]
	s_waitcnt lgkmcnt(0)
	v_add_u32_e32 v213, s48, v176
	ds_read_b128 v[200:203], v213 offset:224
	ds_read_b128 v[214:217], v213 offset:192
	ds_read_b128 v[218:221], v213 offset:160
	ds_read_b128 v[222:225], v213 offset:128
	s_waitcnt lgkmcnt(3)
	v_pk_mul_f32 v[44:45], v[44:45], v[200:201]
	s_waitcnt lgkmcnt(2)
	v_pk_mul_f32 v[40:41], v[40:41], v[214:215]
	s_waitcnt lgkmcnt(1)
	v_pk_mul_f32 v[36:37], v[36:37], v[218:219]
	v_pk_mul_f32 v[46:47], v[46:47], v[202:203]
	v_pk_mul_f32 v[42:43], v[42:43], v[216:217]
	v_pk_mul_f32 v[38:39], v[38:39], v[220:221]
	s_waitcnt lgkmcnt(0)
	v_pk_mul_f32 v[34:35], v[34:35], v[224:225]
	v_pk_mul_f32 v[32:33], v[32:33], v[222:223]
	v_pk_mul_f32 v[60:61], v[60:61], v[200:201]
	v_pk_mul_f32 v[56:57], v[56:57], v[214:215]
	v_pk_mul_f32 v[52:53], v[52:53], v[218:219]
	v_pk_mul_f32 v[62:63], v[62:63], v[202:203]
	v_pk_mul_f32 v[58:59], v[58:59], v[216:217]
	v_pk_mul_f32 v[54:55], v[54:55], v[220:221]
	v_pk_mul_f32 v[50:51], v[50:51], v[224:225]
	v_pk_mul_f32 v[48:49], v[48:49], v[222:223]
	v_pk_mul_f32 v[12:13], v[12:13], v[200:201]
	v_pk_mul_f32 v[8:9], v[8:9], v[214:215]
	v_pk_mul_f32 v[4:5], v[4:5], v[218:219]
	v_pk_mul_f32 v[14:15], v[14:15], v[202:203]
	v_pk_mul_f32 v[10:11], v[10:11], v[216:217]
	v_pk_mul_f32 v[6:7], v[6:7], v[220:221]
	v_pk_mul_f32 v[2:3], v[2:3], v[224:225]
	v_pk_mul_f32 v[0:1], v[0:1], v[222:223]
	v_pk_mul_f32 v[28:29], v[28:29], v[200:201]
	v_pk_mul_f32 v[24:25], v[24:25], v[214:215]
	v_pk_mul_f32 v[20:21], v[20:21], v[218:219]
	v_pk_mul_f32 v[30:31], v[30:31], v[202:203]
	v_pk_mul_f32 v[26:27], v[26:27], v[216:217]
	v_pk_mul_f32 v[22:23], v[22:23], v[220:221]
	v_pk_mul_f32 v[18:19], v[18:19], v[224:225]
	v_pk_mul_f32 v[16:17], v[16:17], v[222:223]
	s_branch .Lh2_tail
